# baseline plus write-through (sc0 sc1) split-K partial stores with the L2 writeback fence dropped from the context publish
# baseline (speedup 1.0000x reference)
;   DEV void quad(int row0, int colbase, int fq, f32x4 (&a)[4][2]) const {
; #pragma unroll
;     for (int m = 0; m < 4; ++m) { (*this)(row0 + m * 16, colbase, fq, a[m][0], a[m][1]); __builtin_amdgcn_sched_barrier(0); }
;   }
.LBB0_827:
	v_readlane_b32 s38, v251, 39
	s_lshl_b32 s41, s41, 7
	s_nop 0
	v_or_b32_e32 v0, s38, v141
	v_readlane_b32 s38, v251, 16
	v_lshl_add_u32 v130, s40, 6, v0
	s_lshl_b32 s40, s38, 2
	v_readlane_b32 s38, v253, 44
	v_readlane_b32 s39, v253, 45
	s_mov_b32 s43, s39
	v_ashrrev_i32_e32 v131, 31, v130
	v_readlane_b32 s38, v251, 12
	v_lshlrev_b64 v[130:131], 12, v[130:131]
	v_readlane_b32 s39, v251, 13
	s_or_b32 s42, s41, s40
	v_lshlrev_b32_e32 v0, 5, v140
	v_lshl_add_u64 v[130:131], s[38:39], 0, v[130:131]
	s_mov_b32 s39, s43
	v_writelane_b32 v253, s38, 44
	v_lshl_add_u64 v[130:131], v[130:131], 0, s[42:43]
	v_lshl_add_u64 v[130:131], v[130:131], 0, v[0:1]
	v_writelane_b32 v253, s39, 45
	s_brev_b32 s38, 63
	s_mov_b32 s39, -1
	v_lshl_add_u64 v[132:133], v[130:131], 0, s[38:39]
	s_brev_b32 s38, 63
	v_add_co_u32_e32 v134, vcc, s38, v130
	s_nop 1
	v_addc_co_u32_e32 v135, vcc, -1, v131, vcc
	global_store_dwordx4 v[134:135], v[122:125], off sc0 sc1
	global_store_dwordx4 v[132:133], v[126:129], off offset:16 sc0 sc1
	s_mov_b32 s38, 0xfc010000
	s_mov_b32 s39, -1
	v_lshl_add_u64 v[122:123], v[130:131], 0, s[38:39]
	s_mov_b32 s38, 0xfc010000
	v_add_co_u32_e32 v124, vcc, s38, v130
	s_nop 1
	v_addc_co_u32_e32 v125, vcc, -1, v131, vcc
	global_store_dwordx4 v[124:125], v[114:117], off sc0 sc1
	global_store_dwordx4 v[122:123], v[118:121], off offset:16 sc0 sc1
	s_mov_b32 s38, 0xfc020000
	s_mov_b32 s39, -1
	v_lshl_add_u64 v[114:115], v[130:131], 0, s[38:39]
	s_mov_b32 s38, 0xfc020000
	v_add_co_u32_e32 v116, vcc, s38, v130
	s_nop 1
	v_addc_co_u32_e32 v117, vcc, -1, v131, vcc
	global_store_dwordx4 v[116:117], v[62:65], off sc0 sc1
	global_store_dwordx4 v[114:115], v[74:77], off offset:16 sc0 sc1
	s_mov_b32 s38, 0xfc030000
	s_mov_b32 s39, -1
	v_lshl_add_u64 v[62:63], v[130:131], 0, s[38:39]
	s_mov_b32 s38, 0xfc030000
	v_add_co_u32_e32 v64, vcc, s38, v130
	s_nop 1
	v_addc_co_u32_e32 v65, vcc, -1, v131, vcc
	global_store_dwordx4 v[64:65], v[2:5], off sc0 sc1
	global_store_dwordx4 v[62:63], v[6:9], off offset:16 sc0 sc1
	global_store_dwordx4 v[132:133], v[58:61], off offset:512 sc0 sc1
	global_store_dwordx4 v[132:133], v[66:69], off offset:528 sc0 sc1
	global_store_dwordx4 v[122:123], v[70:73], off offset:512 sc0 sc1
	global_store_dwordx4 v[122:123], v[78:81], off offset:528 sc0 sc1
	global_store_dwordx4 v[114:115], v[82:85], off offset:512 sc0 sc1
	global_store_dwordx4 v[114:115], v[86:89], off offset:528 sc0 sc1
	global_store_dwordx4 v[62:63], v[90:93], off offset:512 sc0 sc1
	global_store_dwordx4 v[62:63], v[98:101], off offset:528 sc0 sc1
	s_mov_b32 s38, 0xfc080000
	s_mov_b32 s39, -1
	v_lshl_add_u64 v[2:3], v[130:131], 0, s[38:39]
	s_mov_b32 s38, 0xfc080000
	v_add_co_u32_e32 v4, vcc, s38, v130
	s_nop 1
	v_addc_co_u32_e32 v5, vcc, -1, v131, vcc
	global_store_dwordx4 v[4:5], v[106:109], off sc0 sc1
	global_store_dwordx4 v[2:3], v[110:113], off offset:16 sc0 sc1
	s_mov_b32 s38, 0xfc090000
	s_mov_b32 s39, -1
	v_lshl_add_u64 v[4:5], v[130:131], 0, s[38:39]
	s_mov_b32 s38, 0xfc090000
	v_add_co_u32_e32 v6, vcc, s38, v130
	s_nop 1
	v_addc_co_u32_e32 v7, vcc, -1, v131, vcc
	global_store_dwordx4 v[6:7], v[94:97], off sc0 sc1
	global_store_dwordx4 v[4:5], v[102:105], off offset:16 sc0 sc1
	s_mov_b32 s38, 0xfc0a0000
	s_mov_b32 s39, -1
	v_lshl_add_u64 v[6:7], v[130:131], 0, s[38:39]
	s_mov_b32 s38, 0xfc0a0000
	v_add_co_u32_e32 v8, vcc, s38, v130
	s_nop 1
	v_addc_co_u32_e32 v9, vcc, -1, v131, vcc
	global_store_dwordx4 v[8:9], v[46:49], off sc0 sc1
	global_store_dwordx4 v[6:7], v[54:57], off offset:16 sc0 sc1
	s_mov_b32 s38, 0xfc0b0000
	s_mov_b32 s39, -1
	v_lshl_add_u64 v[8:9], v[130:131], 0, s[38:39]
	s_mov_b32 s38, 0xfc0b0000
	v_add_co_u32_e32 v46, vcc, s38, v130
	s_nop 1
	v_addc_co_u32_e32 v47, vcc, -1, v131, vcc
	global_store_dwordx4 v[46:47], v[10:13], off sc0 sc1
	global_store_dwordx4 v[8:9], v[14:17], off offset:16 sc0 sc1
	global_store_dwordx4 v[2:3], v[18:21], off offset:512 sc0 sc1
	global_store_dwordx4 v[2:3], v[22:25], off offset:528 sc0 sc1
	global_store_dwordx4 v[4:5], v[26:29], off offset:512 sc0 sc1
	global_store_dwordx4 v[4:5], v[30:33], off offset:528 sc0 sc1
	global_store_dwordx4 v[6:7], v[34:37], off offset:512 sc0 sc1
	global_store_dwordx4 v[6:7], v[38:41], off offset:528 sc0 sc1
	global_store_dwordx4 v[8:9], v[42:45], off offset:512 sc0 sc1
	global_store_dwordx4 v[8:9], v[50:53], off offset:528 sc0 sc1
	s_mov_b64 s[40:41], 0

; DEV unsigned xb_add(unsigned* p, unsigned v) { return __hip_atomic_fetch_add(p, v, __ATOMIC_RELAXED, __HIP_MEMORY_SCOPE_AGENT); }
;   DEV void quad(int row0, int colbase, int fq, f32x4 (&a)[4][2]) const {
; #pragma unroll
;     for (int m = 0; m < 4; ++m) { (*this)(row0 + m * 16, colbase, fq, a[m][0], a[m][1]); __builtin_amdgcn_sched_barrier(0); }
;   }
; DEV void flag_arrive(unsigned* flag) {
;   asm volatile("s_waitcnt vmcnt(0)" ::: "memory");
;   __syncthreads();
;   if (threadIdx.x == 0) {
;     __builtin_amdgcn_fence(__ATOMIC_RELEASE, "agent");
;     asm volatile("s_waitcnt vmcnt(0)" ::: "memory");
;     xb_add(flag, 1u);
;   }
; }
.LBB0_865:
	v_readlane_b32 s38, v251, 39
	s_lshl_b32 s41, s41, 7
	s_nop 0
	v_or_b32_e32 v0, s38, v141
	v_readlane_b32 s38, v251, 16
	v_lshl_add_u32 v130, s40, 6, v0
	s_lshl_b32 s40, s38, 2
	v_readlane_b32 s38, v253, 44
	v_readlane_b32 s39, v253, 45
	s_mov_b32 s43, s39
	v_ashrrev_i32_e32 v131, 31, v130
	v_readlane_b32 s38, v251, 12
	v_lshlrev_b64 v[130:131], 12, v[130:131]
	v_readlane_b32 s39, v251, 13
	s_or_b32 s42, s41, s40
	v_lshlrev_b32_e32 v0, 5, v140
	v_lshl_add_u64 v[130:131], s[38:39], 0, v[130:131]
	s_mov_b32 s39, s43
	v_writelane_b32 v253, s38, 44
	v_lshl_add_u64 v[130:131], v[130:131], 0, s[42:43]
	v_lshl_add_u64 v[130:131], v[130:131], 0, v[0:1]
	v_writelane_b32 v253, s39, 45
	s_brev_b32 s38, 63
	s_mov_b32 s39, -1
	v_lshl_add_u64 v[132:133], v[130:131], 0, s[38:39]
	s_brev_b32 s38, 63
	v_add_co_u32_e32 v134, vcc, s38, v130
	s_nop 1
	v_addc_co_u32_e32 v135, vcc, -1, v131, vcc
	global_store_dwordx4 v[134:135], v[122:125], off sc0 sc1
	global_store_dwordx4 v[132:133], v[126:129], off offset:16 sc0 sc1
	s_mov_b32 s38, 0xfc010000
	s_mov_b32 s39, -1
	v_lshl_add_u64 v[122:123], v[130:131], 0, s[38:39]
	s_mov_b32 s38, 0xfc010000
	v_add_co_u32_e32 v124, vcc, s38, v130
	s_nop 1
	v_addc_co_u32_e32 v125, vcc, -1, v131, vcc
	global_store_dwordx4 v[124:125], v[114:117], off sc0 sc1
	global_store_dwordx4 v[122:123], v[118:121], off offset:16 sc0 sc1
	s_mov_b32 s38, 0xfc020000
	s_mov_b32 s39, -1
	v_lshl_add_u64 v[114:115], v[130:131], 0, s[38:39]
	s_mov_b32 s38, 0xfc020000
	v_add_co_u32_e32 v116, vcc, s38, v130
	s_nop 1
	v_addc_co_u32_e32 v117, vcc, -1, v131, vcc
	global_store_dwordx4 v[116:117], v[62:65], off sc0 sc1
	global_store_dwordx4 v[114:115], v[74:77], off offset:16 sc0 sc1
	s_mov_b32 s38, 0xfc030000
	s_mov_b32 s39, -1
	v_lshl_add_u64 v[62:63], v[130:131], 0, s[38:39]
	s_mov_b32 s38, 0xfc030000
	v_add_co_u32_e32 v64, vcc, s38, v130
	s_nop 1
	v_addc_co_u32_e32 v65, vcc, -1, v131, vcc
	global_store_dwordx4 v[64:65], v[2:5], off sc0 sc1
	global_store_dwordx4 v[62:63], v[6:9], off offset:16 sc0 sc1
	global_store_dwordx4 v[132:133], v[58:61], off offset:512 sc0 sc1
	global_store_dwordx4 v[132:133], v[66:69], off offset:528 sc0 sc1
	global_store_dwordx4 v[122:123], v[70:73], off offset:512 sc0 sc1
	global_store_dwordx4 v[122:123], v[78:81], off offset:528 sc0 sc1
	global_store_dwordx4 v[114:115], v[82:85], off offset:512 sc0 sc1
	global_store_dwordx4 v[114:115], v[86:89], off offset:528 sc0 sc1
	global_store_dwordx4 v[62:63], v[90:93], off offset:512 sc0 sc1
	global_store_dwordx4 v[62:63], v[98:101], off offset:528 sc0 sc1
	s_mov_b32 s38, 0xfc080000
	s_mov_b32 s39, -1
	v_lshl_add_u64 v[2:3], v[130:131], 0, s[38:39]
	s_mov_b32 s38, 0xfc080000
	v_add_co_u32_e32 v4, vcc, s38, v130
	s_nop 1
	v_addc_co_u32_e32 v5, vcc, -1, v131, vcc
	global_store_dwordx4 v[4:5], v[106:109], off sc0 sc1
	global_store_dwordx4 v[2:3], v[110:113], off offset:16 sc0 sc1
	s_mov_b32 s38, 0xfc090000
	s_mov_b32 s39, -1
	v_lshl_add_u64 v[4:5], v[130:131], 0, s[38:39]
	s_mov_b32 s38, 0xfc090000
	v_add_co_u32_e32 v6, vcc, s38, v130
	s_nop 1
	v_addc_co_u32_e32 v7, vcc, -1, v131, vcc
	global_store_dwordx4 v[6:7], v[94:97], off sc0 sc1
	global_store_dwordx4 v[4:5], v[102:105], off offset:16 sc0 sc1
	s_mov_b32 s38, 0xfc0a0000
	s_mov_b32 s39, -1
	v_lshl_add_u64 v[6:7], v[130:131], 0, s[38:39]
	s_mov_b32 s38, 0xfc0a0000
	v_add_co_u32_e32 v8, vcc, s38, v130
	s_nop 1
	v_addc_co_u32_e32 v9, vcc, -1, v131, vcc
	global_store_dwordx4 v[8:9], v[46:49], off sc0 sc1
	global_store_dwordx4 v[6:7], v[54:57], off offset:16 sc0 sc1
	s_mov_b32 s38, 0xfc0b0000
	s_mov_b32 s39, -1
	v_lshl_add_u64 v[8:9], v[130:131], 0, s[38:39]
	s_mov_b32 s38, 0xfc0b0000
	v_add_co_u32_e32 v46, vcc, s38, v130
	s_nop 1
	v_addc_co_u32_e32 v47, vcc, -1, v131, vcc
	global_store_dwordx4 v[46:47], v[10:13], off sc0 sc1
	global_store_dwordx4 v[8:9], v[14:17], off offset:16 sc0 sc1
	global_store_dwordx4 v[2:3], v[18:21], off offset:512 sc0 sc1
	global_store_dwordx4 v[2:3], v[22:25], off offset:528 sc0 sc1
	global_store_dwordx4 v[4:5], v[26:29], off offset:512 sc0 sc1
	global_store_dwordx4 v[4:5], v[30:33], off offset:528 sc0 sc1
	global_store_dwordx4 v[6:7], v[34:37], off offset:512 sc0 sc1
	global_store_dwordx4 v[6:7], v[38:41], off offset:528 sc0 sc1
	global_store_dwordx4 v[8:9], v[42:45], off offset:512 sc0 sc1
	global_store_dwordx4 v[8:9], v[50:53], off offset:528 sc0 sc1
.LBB0_866:
	s_waitcnt vmcnt(0)
	s_waitcnt vmcnt(0)
	s_barrier
	s_mov_b64 s[40:41], exec
	v_readlane_b32 s42, v250, 1
	v_readlane_b32 s43, v250, 2
	s_and_b64 s[42:43], s[40:41], s[42:43]
	s_mov_b64 exec, s[42:43]
	s_cbranch_execz .LBB0_883
	v_readlane_b32 s38, v253, 44
	v_readlane_b32 s39, v253, 45
	s_mov_b32 s43, s39
	s_lshl_b32 s42, s52, 3
	v_writelane_b32 v253, s38, 44
	s_lshl_b64 s[42:43], s[42:43], 2
	s_add_u32 s42, s53, s42
	v_writelane_b32 v253, s39, 45
	s_addc_u32 s43, s54, s43
	v_readlane_b32 s38, v253, 39
	s_lshl_b32 s44, s38, 2
	s_add_u32 s42, s42, s44
	s_mov_b64 s[44:45], exec
	s_waitcnt vmcnt(0)
	v_mbcnt_lo_u32_b32 v0, s44, 0
	v_mbcnt_hi_u32_b32 v0, s45, v0
	s_addc_u32 s43, s43, 0
	v_cmp_eq_u32_e32 vcc, 0, v0
	s_and_saveexec_b64 s[48:49], vcc
	s_cbranch_execz .LBB0_869
	s_bcnt1_i32_b64 s44, s[44:45]
	v_mov_b32_e32 v0, s44
	global_atomic_add v1, v0, s[42:43] offset:-32

; DEV int vblock() { const int G = gridDim.x, bx = blockIdx.x; return (G % 8 == 0) ? (bx % 8) * (G / 8) + bx / 8 : bx; }
; template <class Epi>
; DEV void gemm_phase(const bf16* A, int lda, const bf16* Bt, int ldb, int M, int N, int K, Epi epi) {
;   const int nM = M / 256, nN = N / 256, ntile = nM * nN;
;   for (int t = vblock(); t < ntile; t += gridDim.x) {
;     int pm, pn; tile_of(t, nM, nN, pm, pn);
; DEV void run_phase(const Params& p, int ph) {
;     ...
;     case 0: case 10: {
;       const int j = (k == 0) ? 0 : 1;
;       const int M = (last && j == 1) ? TL : T;
;       gemm_phase(j == 0 ? H : reinterpret_cast<const bf16*>(ws + O_H2), 1024, WFI + (size_t)j * 5632 * 1024, 1024, M, 5632, 1024, EpiSwiglu{PROJ});
.LBB0_954:
	v_readlane_b32 s8, v254, 58
	s_cmp_lg_u32 s8, 0
	s_cselect_b64 s[0:1], -1, 0
	s_cmp_eq_u32 s8, 0
	v_readlane_b32 s8, v254, 59
	v_readlane_b32 s9, v254, 60
	s_cselect_b64 s[40:41], -1, 0
	s_and_b64 s[42:43], s[8:9], s[0:1]
	s_and_b64 s[42:43], s[42:43], exec
	s_cselect_b32 s48, 64, 0x48
	s_mul_i32 s44, s48, 22
	s_cmp_ge_i32 s45, s44
	s_cbranch_scc1 .LBB0_963
	s_and_b64 s[0:1], s[0:1], exec
	v_readlane_b32 s0, v250, 3
	v_readlane_b32 s1, v250, 4
	v_readlane_b32 s42, v252, 5
	s_cselect_b32 s49, s42, s1
	v_readlane_b32 s1, v252, 4
	s_cselect_b32 s50, s1, s0
	s_cselect_b32 s0, 0xb00000, 0
	v_readlane_b32 s8, v255, 3
	v_readlane_b32 s9, v255, 4
	s_add_u32 s51, s8, s0
	s_addc_u32 s52, s9, 0
	v_readlane_b32 s1, v254, 63
	s_add_u32 s0, s1, s0
	s_addc_u32 s1, 0, 0
	s_add_u32 s53, s88, s0
	s_addc_u32 s54, s89, s1
	s_waitcnt vmcnt(0)
	s_branch .LBB0_957

; #define STAGE(P, BASE, LD, br, kt) do { const bf16* _gb = BASE + ((long)(br) * (LD) + (long)(kt) * BK); \
;     _Pragma("unroll") for (int _i = 0; _i < 2; ++_i) { \
;       __builtin_amdgcn_global_load_lds((const unsigned*)(_gb + ((&LD == &lda) ? offA[_i] : offB[_i])), \
;         (unsigned*)((char*)(P) + tidx_ * 16 + _i * 8192), 16, 0, 0); } } while (0)
; DEV int vblock() { const int G = gridDim.x, bx = blockIdx.x; return (G % 8 == 0) ? (bx % 8) * (G / 8) + bx / 8 : bx; }
; template <class Epi, int NB>
; DEV void gemm_tile_nb(const bf16* __restrict__ A, int lda, long strideA, const bf16* __restrict__ Bt, int ldb, long strideB, int K, int brow, int bcol, Epi& epi) {
;     ...
;   const int lane_off_ = (fr * 64 + fq * 16) ^ ((fr >> 3) << 5);
;   const int aoff = wr * 8192 + lane_off_, boff = 65536 + wc * 4096 + lane_off_;
;   unsigned offA[2], offB[2];
; #pragma unroll
;   for (int _i = 0; _i < 2; ++_i) { int _r, _c; stage_rc(tidx_ * 16 + _i * 8192, _r, _c); offA[_i] = (unsigned)(_r * lda + _c); offB[_i] = (unsigned)(_r * ldb + _c); }
; #pragma unroll 1
;   for (int br = 0; br < NB; ++br) {
;   STAGE(SB(0, 0), Bt, ldb, bcol, 0); STAGE(SA(0, 0), A, lda, brow, 0);
;   STAGE(SB(0, 1), Bt, ldb, bcol + HALF, 0); STAGE(SA(0, 1), A, lda, brow + HALF, 0);
; template <class Epi>
; DEV void gemm_phase(const bf16* A, int lda, const bf16* Bt, int ldb, int M, int N, int K, Epi epi) {
;   const int nM = M / 256, nN = N / 256, ntile = nM * nN;
;   for (int t = vblock(); t < ntile; t += gridDim.x) {
;     int pm, pn; tile_of(t, nM, nN, pm, pn);
;     gemm_tile(A, lda, Bt, ldb, K, pm * 256, pn * 256, epi);
.LBB0_957:
	s_mul_hi_i32 s0, s45, 0x2e8ba2e9
	s_lshr_b32 s1, s0, 31
	s_ashr_i32 s58, s0, 5
	s_add_i32 s58, s58, s1
	s_lshl_b32 s42, s58, 3
	s_sub_i32 s0, s48, s42
	s_min_i32 s43, s0, 8
	s_sext_i32_i16 s1, s43
	v_cvt_f32_i32_e32 v0, s1
	s_mul_i32 s0, s58, 0xb0
	s_sub_i32 s56, s45, s0
	s_sext_i32_i16 s0, s56
	v_cvt_f32_i32_e32 v2, s0
	v_rcp_iflag_f32_e32 v3, v0
	s_xor_b32 s0, s0, s1
	s_ashr_i32 s0, s0, 30
	s_or_b32 s55, s0, 1
	v_mul_f32_e32 v3, v2, v3
	v_trunc_f32_e32 v3, v3
	v_fma_f32 v2, -v3, v0, v2
	v_cmp_ge_f32_e64 s[0:1], |v2|, |v0|
	v_mov_b32 v23, v179
	v_cvt_i32_f32_e32 v3, v3
	v_ashrrev_i32_e32 v0, 31, v23
	v_lshrrev_b32_e32 v0, 26, v0
	v_add_u32_e32 v0, v23, v0
	v_ashrrev_i32_e32 v14, 6, v0
	v_bfe_i32 v0, v23, 27, 1
	v_lshlrev_b32_e32 v15, 4, v23
	v_lshrrev_b32_e32 v0, 22, v0
	v_add_u32_e32 v0, v15, v0
	v_and_b32_e32 v0, 0xfffffc00, v0
	v_sub_u32_e32 v0, v15, v0
	v_lshrrev_b32_e32 v2, 4, v0
	v_bitop3_b32 v2, v2, v0, 32 bitop3:0x6c
	v_ashrrev_i32_e32 v0, 31, v0
	s_and_b64 s[0:1], s[0:1], exec
	v_lshrrev_b32_e32 v0, 26, v0
	v_readfirstlane_b32 s1, v3
	v_lshlrev_b32_e32 v3, 3, v14
	v_add_u32_e32 v0, v2, v0
	v_and_b32_e32 v3, 0x3ffff0, v3
	v_ashrrev_i32_e32 v16, 6, v0
	v_add_u32_e32 v0, v16, v3
	v_lshlrev_b32_e32 v3, 5, v14
	v_and_b32_e32 v17, 32, v3
	v_mul_i32_i24_e32 v3, 64, v16
	v_sub_u32_e32 v2, v2, v3
	v_ashrrev_i16_sdwa v19, v207, sext(v2) dst_sel:DWORD dst_unused:UNUSED_PAD src0_sel:DWORD src1_sel:BYTE_0
	v_add_u32_e32 v2, 0x2000, v15
	v_ashrrev_i32_e32 v3, 31, v2
	v_lshrrev_b32_e32 v3, 22, v3
	v_add_u32_e32 v3, v2, v3
	v_ashrrev_i32_e32 v18, 10, v3
	s_cselect_b32 s0, s55, 0
	v_mul_i32_i24_e32 v3, 0x400, v18
	s_add_i32 s0, s1, s0
	v_sub_u32_e32 v2, v2, v3
	s_sext_i32_i16 s55, s0
	s_mul_i32 s0, s0, s43
	v_lshrrev_b32_e32 v3, 4, v2
	s_sub_i32 s0, s56, s0
	v_bitop3_b32 v2, v3, v2, 32 bitop3:0x6c
	s_sext_i32_i16 s59, s0
	s_lshl_b32 s60, s55, 8
	v_ashrrev_i32_e32 v4, 31, v2
	s_add_i32 s42, s42, s59
	v_readfirstlane_b32 s57, v23
	v_lshrrev_b32_e32 v4, 26, v4
	s_ashr_i32 s61, s60, 31
	s_lshl_b32 s0, s42, 8
	s_ashr_i32 s56, s57, 8
	v_lshlrev_b32_e32 v3, 3, v18
	v_add_u32_e32 v4, v2, v4
	s_lshl_b64 s[42:43], s[60:61], 11
	v_and_b32_e32 v3, 0x3ffff0, v3
	v_ashrrev_i32_e32 v20, 6, v4
	v_lshlrev_b32_e32 v5, 5, v18
	v_and_b32_e32 v4, 0xc0, v4
	s_add_u32 s62, s51, s42
	v_lshl_or_b32 v0, v0, 10, v17
	v_add_u32_e32 v3, v20, v3
	v_and_b32_e32 v21, 32, v5
	v_sub_u32_e32 v2, v2, v4
	s_addc_u32 s63, s52, s43
	s_bitset1_b32 s60, 7
	s_or_b32 s68, s0, 0x80
	v_add_u32_sdwa v0, v0, sext(v19) dst_sel:DWORD dst_unused:UNUSED_PAD src0_sel:DWORD src1_sel:WORD_0
	v_ashrrev_i16_sdwa v22, v207, sext(v2) dst_sel:DWORD dst_unused:UNUSED_PAD src0_sel:DWORD src1_sel:BYTE_0
	v_lshl_or_b32 v2, v3, 10, v21
	v_add_u32_e32 v144, s74, v15
	s_ashr_i32 s1, s0, 31
	s_ashr_i32 s61, s60, 31
	s_ashr_i32 s69, s68, 31
	v_add_u32_sdwa v4, v2, sext(v22) dst_sel:DWORD dst_unused:UNUSED_PAD src0_sel:DWORD src1_sel:WORD_0
	s_lshl_b64 s[64:65], s[0:1], 11
	s_lshl_b64 s[60:61], s[60:61], 11
	s_lshl_b64 s[68:69], s[68:69], 11
	v_lshlrev_b64 v[24:25], 1, v[0:1]
	v_readfirstlane_b32 s1, v144
	v_mov_b32_e32 v5, v1
	v_add_u32_e32 v148, 0x2000, v144
	s_add_u32 s64, s50, s64
	v_add_u32_e32 v146, 0, v15
	v_lshl_add_u64 v[2:3], s[62:63], 0, v[24:25]
	s_mov_b32 m0, s1
	v_lshlrev_b64 v[26:27], 1, v[4:5]
	v_readfirstlane_b32 s1, v148
	s_addc_u32 s65, s49, s65
	global_load_lds_dwordx4 v[2:3], off
	v_lshl_add_u64 v[6:7], s[62:63], 0, v[26:27]
	s_mov_b32 m0, s1
	v_readfirstlane_b32 s1, v146
	v_add_u32_e32 v150, 0x2000, v146
	s_add_u32 s60, s51, s60
	v_add_u32_e32 v147, s12, v15
	global_load_lds_dwordx4 v[6:7], off
	v_lshl_add_u64 v[12:13], s[64:65], 0, v[24:25]
	s_mov_b32 m0, s1
	v_readfirstlane_b32 s1, v150
	s_addc_u32 s61, s52, s61
	global_load_lds_dwordx4 v[12:13], off
	v_lshl_add_u64 v[8:9], s[64:65], 0, v[26:27]
	s_mov_b32 m0, s1
	v_readfirstlane_b32 s1, v147
	v_add_u32_e32 v151, 0x2000, v147
	s_add_u32 s68, s50, s68
	v_add_u32_e32 v149, 0x4000, v146
	global_load_lds_dwordx4 v[8:9], off
	v_lshl_add_u64 v[10:11], s[60:61], 0, v[24:25]
	s_mov_b32 m0, s1
	v_readfirstlane_b32 s1, v151
	s_addc_u32 s69, s49, s69
	global_load_lds_dwordx4 v[10:11], off
	v_lshl_add_u64 v[4:5], s[60:61], 0, v[26:27]
	s_mov_b32 m0, s1
	v_readfirstlane_b32 s1, v149
	v_add_u32_e32 v152, 0x6000, v146
	global_load_lds_dwordx4 v[4:5], off
	v_lshl_add_u64 v[132:133], s[68:69], 0, v[24:25]
	s_mov_b32 m0, s1
	v_readfirstlane_b32 s1, v152
	global_load_lds_dwordx4 v[132:133], off
	v_lshl_add_u64 v[130:131], s[68:69], 0, v[26:27]
	s_mov_b32 m0, s1
	s_cmp_lg_u32 s56, 1
	global_load_lds_dwordx4 v[130:131], off
	s_cbranch_scc1 .LBB0_959
	s_barrier
; #define STAGE(P, BASE, LD, br, kt) do { const bf16* _gb = BASE + ((long)(br) * (LD) + (long)(kt) * BK); \
;     _Pragma("unroll") for (int _i = 0; _i < 2; ++_i) { \
;       __builtin_amdgcn_global_load_lds((const unsigned*)(_gb + ((&LD == &lda) ? offA[_i] : offB[_i])), \
;         (unsigned*)((char*)(P) + tidx_ * 16 + _i * 8192), 16, 0, 0); } } while (0)
; #define WAIT_V(n) asm volatile("s_waitcnt vmcnt(" #n ")" ::: "memory")
; #define BAR __builtin_amdgcn_s_barrier()
; template <class Epi, int NB>
; DEV void gemm_tile_nb(const bf16* __restrict__ A, int lda, long strideA, const bf16* __restrict__ Bt, int ldb, long strideB, int K, int brow, int bcol, Epi& epi) {
;     ...
;   const int wid = __builtin_amdgcn_readfirstlane(tidx_ >> 6), lane = tidx_ & 63, wr = wid >> 2, wc = wid & 3, fr = lane & 15, fq = lane >> 4;
;   f32x4 acc[2][2][4][2] = {};
;   bf16x8 At[4][2], B0[2][2], B1[2][2];
;   const int nt = K / BK;
;   const int lane_off_ = (fr * 64 + fq * 16) ^ ((fr >> 3) << 5);
;   const int aoff = wr * 8192 + lane_off_, boff = 65536 + wc * 4096 + lane_off_;
;   unsigned offA[2], offB[2];
; #pragma unroll
;   for (int _i = 0; _i < 2; ++_i) { int _r, _c; stage_rc(tidx_ * 16 + _i * 8192, _r, _c); offA[_i] = (unsigned)(_r * lda + _c); offB[_i] = (unsigned)(_r * ldb + _c); }
; #pragma unroll 1
;   for (int br = 0; br < NB; ++br) {
;   STAGE(SB(0, 0), Bt, ldb, bcol, 0); STAGE(SA(0, 0), A, lda, brow, 0);
;   STAGE(SB(0, 1), Bt, ldb, bcol + HALF, 0); STAGE(SA(0, 1), A, lda, brow + HALF, 0);
;   if (wr == 1) BAR;
;   WAIT_V(4); BAR;
;   STAGE(SB(1, 0), Bt, ldb, bcol, 1); STAGE(SA(1, 0), A, lda, brow, 1); STAGE(SB(1, 1), Bt, ldb, bcol + HALF, 1);
;   WAIT_V(6); BAR;
.LBB0_959:
	v_and_b32_e32 v143, 15, v23
	s_bfe_u32 s1, s57, 0x20006
	v_bfe_u32 v142, v23, 4, 2
	v_lshlrev_b32_e32 v0, 6, v143
	v_lshlrev_b32_e32 v23, 2, v23
	v_lshl_or_b32 v0, v142, 4, v0
	v_and_b32_e32 v23, 32, v23
	s_lshl_b32 s60, s56, 13
	s_lshl_b32 s61, s1, 12
	v_add_u32_e32 v153, s13, v15
	v_bitop3_b32 v24, v0, s61, v23 bitop3:0xde
	v_bitop3_b32 v23, v0, s60, v23 bitop3:0xde
	s_mov_b64 s[62:63], 0x80
	v_readfirstlane_b32 s60, v153
	v_add_u32_e32 v154, 0x2000, v153
	v_lshl_add_u64 v[2:3], v[2:3], 0, s[62:63]
	s_mov_b32 m0, s60
	v_readfirstlane_b32 s60, v154
	v_add_u32_e32 v155, 0x8000, v146
	s_waitcnt vmcnt(4)
	s_barrier
	global_load_lds_dwordx4 v[2:3], off
	v_lshl_add_u64 v[2:3], v[6:7], 0, s[62:63]
	s_mov_b32 m0, s60
	v_readfirstlane_b32 s60, v155
	v_add_u32_e32 v156, 0xa000, v146
	global_load_lds_dwordx4 v[2:3], off
	v_lshl_add_u64 v[2:3], v[12:13], 0, s[62:63]
	s_mov_b32 m0, s60
	v_readfirstlane_b32 s60, v156
	v_add_u32_e32 v157, s14, v15
	global_load_lds_dwordx4 v[2:3], off
	v_lshl_add_u64 v[2:3], v[8:9], 0, s[62:63]
	s_mov_b32 m0, s60
	v_readfirstlane_b32 s60, v157
	v_add_u32_e32 v158, 0x2000, v157
	global_load_lds_dwordx4 v[2:3], off
	v_lshl_add_u64 v[2:3], v[10:11], 0, s[62:63]
	s_mov_b32 m0, s60
	v_readfirstlane_b32 s60, v158
	global_load_lds_dwordx4 v[2:3], off
	v_lshl_add_u64 v[2:3], v[4:5], 0, s[62:63]
	s_mov_b32 m0, s60
	v_lshlrev_b32_e32 v0, 13, v14
	global_load_lds_dwordx4 v[2:3], off
	v_and_b32_e32 v0, 0xffffc000, v0
	v_lshl_add_u32 v0, v16, 10, v0
	v_or_b32_e32 v0, v0, v17
	v_add_u32_sdwa v0, v0, sext(v19) dst_sel:DWORD dst_unused:UNUSED_PAD src0_sel:DWORD src1_sel:WORD_0
	v_lshlrev_b64 v[2:3], 1, v[0:1]
	v_lshlrev_b32_e32 v0, 13, v18
	v_and_b32_e32 v0, 0xffffc000, v0
	v_lshl_add_u32 v0, v20, 10, v0
	v_or_b32_e32 v0, v0, v21
	s_add_u32 s42, s53, s42
	v_add_u32_sdwa v0, v0, sext(v22) dst_sel:DWORD dst_unused:UNUSED_PAD src0_sel:DWORD src1_sel:WORD_0
	s_addc_u32 s43, s54, s43
	v_lshlrev_b64 v[4:5], 1, v[0:1]
	v_lshl_add_u64 v[134:135], s[42:43], 0, v[2:3]
	v_lshl_add_u64 v[136:137], s[42:43], 0, v[4:5]
	s_lshl_b32 s42, s58, 11
	s_lshl_b32 s43, s59, 8
	s_add_i32 s42, s42, s43
	s_ashr_i32 s43, s42, 31
	s_lshl_b64 s[42:43], s[42:43], 11
	s_add_u32 s42, s50, s42
	s_waitcnt vmcnt(6)
	s_addc_u32 s43, s49, s43
	v_or_b32_e32 v24, 0x10000, v24
	v_lshl_add_u64 v[138:139], s[42:43], 0, v[2:3]
	v_mov_b32_e32 v2, 0
	v_lshl_add_u64 v[140:141], s[42:43], 0, v[4:5]
	s_mov_b32 s58, -2
	s_mov_b64 s[42:43], 0
	v_add_u32_e32 v145, 0, v24
	v_add_u32_e32 v0, 0, v23
	v_mov_b32_e32 v3, v2
	v_mov_b32_e32 v4, v2
	v_mov_b32_e32 v5, v2
	v_mov_b32_e32 v6, v2
	v_mov_b32_e32 v7, v2
	v_mov_b32_e32 v8, v2
	v_mov_b32_e32 v9, v2
	v_mov_b32_e32 v10, v2
	v_mov_b32_e32 v11, v2
	v_mov_b32_e32 v12, v2
	v_mov_b32_e32 v13, v2
	v_mov_b32_e32 v14, v2
	v_mov_b32_e32 v15, v2
	v_mov_b32_e32 v16, v2
	v_mov_b32_e32 v17, v2
	v_mov_b32_e32 v18, v2
	v_mov_b32_e32 v19, v2
	v_mov_b32_e32 v20, v2
	v_mov_b32_e32 v21, v2
	v_mov_b32_e32 v22, v2
	v_mov_b32_e32 v23, v2
	v_mov_b32_e32 v24, v2
	v_mov_b32_e32 v25, v2
	v_mov_b32_e32 v26, v2
	v_mov_b32_e32 v27, v2
	v_mov_b32_e32 v28, v2
	v_mov_b32_e32 v29, v2
	v_mov_b32_e32 v30, v2
	v_mov_b32_e32 v31, v2
	v_mov_b32_e32 v32, v2
	v_mov_b32_e32 v33, v2
	v_mov_b32_e32 v34, v2
	v_mov_b32_e32 v35, v2
	v_mov_b32_e32 v36, v2
	v_mov_b32_e32 v37, v2
	v_mov_b32_e32 v38, v2
	v_mov_b32_e32 v39, v2
	v_mov_b32_e32 v40, v2
	v_mov_b32_e32 v41, v2
	v_mov_b32_e32 v42, v2
	v_mov_b32_e32 v43, v2
	v_mov_b32_e32 v44, v2
	v_mov_b32_e32 v45, v2
	v_mov_b32_e32 v46, v2
	v_mov_b32_e32 v47, v2
	v_mov_b32_e32 v48, v2
	v_mov_b32_e32 v49, v2
	v_mov_b32_e32 v50, v2
	v_mov_b32_e32 v51, v2
	v_mov_b32_e32 v52, v2
	v_mov_b32_e32 v53, v2
	v_mov_b32_e32 v54, v2
	v_mov_b32_e32 v55, v2
	v_mov_b32_e32 v56, v2
	v_mov_b32_e32 v57, v2
	v_mov_b32_e32 v58, v2
	v_mov_b32_e32 v59, v2
	v_mov_b32_e32 v60, v2
	v_mov_b32_e32 v61, v2
	v_mov_b32_e32 v62, v2
	v_mov_b32_e32 v63, v2
	v_mov_b32_e32 v64, v2
	v_mov_b32_e32 v65, v2
	v_mov_b32_e32 v70, v2
	v_mov_b32_e32 v71, v2
	v_mov_b32_e32 v72, v2
	v_mov_b32_e32 v73, v2
	v_mov_b32_e32 v86, v2
	v_mov_b32_e32 v87, v2
	v_mov_b32_e32 v88, v2
	v_mov_b32_e32 v89, v2
	v_mov_b32_e32 v90, v2
	v_mov_b32_e32 v91, v2
	v_mov_b32_e32 v92, v2
	v_mov_b32_e32 v93, v2
	v_mov_b32_e32 v94, v2
	v_mov_b32_e32 v95, v2
	v_mov_b32_e32 v96, v2
	v_mov_b32_e32 v97, v2
	v_mov_b32_e32 v98, v2
	v_mov_b32_e32 v99, v2
	v_mov_b32_e32 v100, v2
	v_mov_b32_e32 v101, v2
	v_mov_b32_e32 v102, v2
	v_mov_b32_e32 v103, v2
	v_mov_b32_e32 v104, v2
	v_mov_b32_e32 v105, v2
	v_mov_b32_e32 v106, v2
	v_mov_b32_e32 v107, v2
	v_mov_b32_e32 v108, v2
	v_mov_b32_e32 v109, v2
	v_mov_b32_e32 v110, v2
	v_mov_b32_e32 v111, v2
	v_mov_b32_e32 v112, v2
	v_mov_b32_e32 v113, v2
	v_mov_b32_e32 v114, v2
	v_mov_b32_e32 v115, v2
	v_mov_b32_e32 v116, v2
	v_mov_b32_e32 v117, v2
	v_mov_b32_e32 v118, v2
	v_mov_b32_e32 v119, v2
	v_mov_b32_e32 v120, v2
	v_mov_b32_e32 v121, v2
	v_mov_b32_e32 v122, v2
	v_mov_b32_e32 v123, v2
	v_mov_b32_e32 v124, v2
	v_mov_b32_e32 v125, v2
	v_mov_b32_e32 v126, v2
	v_mov_b32_e32 v127, v2
	v_mov_b32_e32 v128, v2
	v_mov_b32_e32 v129, v2
	v_mov_b32_e32 v66, v2
	v_mov_b32_e32 v67, v2
	v_mov_b32_e32 v68, v2
	v_mov_b32_e32 v69, v2
	v_mov_b32_e32 v74, v2
	v_mov_b32_e32 v75, v2
	v_mov_b32_e32 v76, v2
	v_mov_b32_e32 v77, v2
	v_mov_b32_e32 v78, v2
	v_mov_b32_e32 v79, v2
	v_mov_b32_e32 v80, v2
	v_mov_b32_e32 v81, v2
	v_mov_b32_e32 v82, v2
	v_mov_b32_e32 v83, v2
	v_mov_b32_e32 v84, v2
	v_mov_b32_e32 v85, v2
	s_barrier
